# post-finish barrier replaced by per-token-tile completion counters (write-through Y stores; OUT tile waits only for its own 4 finish units)
# baseline (speedup 1.0000x reference)
; __device__ __forceinline__ void lru_finish3(const Args& a, int l, int bx, int G, LAS unsigned char* lds) {
;     ...
;             u32x4 f0[4], f1[4], b0[4], b1[4], gq[4];
; #pragma unroll
;             for (int q = 0; q < 4; ++q) { const int rl = wave * 8 + it * 4 + q; const size_t row = (size_t)b * SEQ + ch0 * 32 + rl;
;                 const unsigned* hpf = HP + row * LW + lane * 8; const unsigned* hpb = hpf + (size_t)T * LW;
;                 f0[q] = *(const u32x4*)hpf; f1[q] = *(const u32x4*)(hpf + 4); b0[q] = *(const u32x4*)hpb; b1[q] = *(const u32x4*)(hpb + 4);
;                 gq[q] = *(const u32x4*)(proj + row * DIN + LW + lane * 8); }
;             asm volatile("" ::: "memory");
; #pragma unroll
;             for (int q = 0; q < 4; ++q) { const int rl = wave * 8 + it * 4 + q; const size_t row = (size_t)b * SEQ + ch0 * 32 + rl;
;                 float y[8]; float s = 0.f;
; #pragma unroll
;                 for (int i = 0; i < 8; ++i) {
;                     const unsigned fw = i < 4 ? f0[q][i & 3] : f1[q][i & 3], bw = i < 4 ? b0[q][i & 3] : b1[q][i & 3], gw2 = gq[q][i >> 1];
;                     const float cfi = i < 4 ? cf0[i & 3] : cf1[i & 3], cbi = i < 4 ? cb0[i & 3] : cb1[i & 3];
;                     const float hlf = __builtin_bit_cast(float, fw << 16), pf_ = __builtin_bit_cast(float, fw & 0xffff0000u);
;                     const float hlb = __builtin_bit_cast(float, bw << 16), pb_ = __builtin_bit_cast(float, bw & 0xffff0000u);
;                     const float g = __builtin_bit_cast(float, (i & 1) ? (gw2 & 0xffff0000u) : (gw2 << 16));
;                     y[i] = gelu_tanh(g) * ((hlf + pf_ * cfi) + (hlb + pb_ * cbi)); s += y[i] * y[i]; }
.LBB0_310:
	s_or_b32 s38, s63, s28
	v_cndmask_b32_e64 v18, 0, 1, s[0:1]
	s_ashr_i32 s1, s38, 31
	s_add_u32 s0, s47, s38
	s_addc_u32 s1, s62, s1
	s_lshl_b64 s[44:45], s[0:1], 11
	s_mulk_i32 s1, 0xe00
	s_mul_hi_u32 s39, s0, 0xe00
	s_add_i32 s39, s39, s1
	s_mulk_i32 s0, 0xe00
	s_add_u32 s60, s50, s0
	s_addc_u32 s61, s51, s39
	s_or_b32 s0, s38, 1
	s_ashr_i32 s1, s0, 31
	s_add_u32 s0, s47, s0
	s_addc_u32 s1, s62, s1
	s_lshl_b64 s[42:43], s[0:1], 11
	s_mulk_i32 s1, 0xe00
	s_mul_hi_u32 s39, s0, 0xe00
	s_add_i32 s39, s39, s1
	s_mulk_i32 s0, 0xe00
	s_add_u32 s64, s50, s0
	s_addc_u32 s65, s51, s39
	s_or_b32 s0, s38, 2
	s_ashr_i32 s1, s0, 31
	s_add_u32 s0, s47, s0
	s_addc_u32 s1, s62, s1
	s_lshl_b64 s[40:41], s[0:1], 11
	s_mulk_i32 s1, 0xe00
	s_mul_hi_u32 s39, s0, 0xe00
	s_add_i32 s39, s39, s1
	s_mulk_i32 s0, 0xe00
	s_add_u32 s66, s50, s0
	s_addc_u32 s67, s51, s39
	s_or_b32 s0, s38, 3
	s_ashr_i32 s1, s0, 31
	s_add_u32 s38, s47, s0
	s_addc_u32 s39, s62, s1
	s_lshl_b64 s[0:1], s[38:39], 11
	s_mulk_i32 s39, 0xe00
	s_mul_hi_u32 s59, s38, 0xe00
	s_add_i32 s59, s59, s39
	s_mulk_i32 s38, 0xe00
	v_cmp_ne_u32_e32 vcc, 1, v18
	v_lshl_add_u64 v[18:19], v[104:105], 0, s[44:45]
	s_add_u32 s70, s50, s38
	v_lshl_add_u64 v[22:23], v[18:19], 0, s[54:55]
	global_load_dwordx4 v[82:85], v[18:19], off offset:16
	global_load_dwordx4 v[94:97], v[18:19], off
	v_add_co_u32_e64 v18, s[38:39], s56, v18
	s_addc_u32 s71, s51, s59
	s_nop 0
	v_addc_co_u32_e64 v19, s[38:39], 0, v19, s[38:39]
	global_load_dwordx4 v[98:101], v[18:19], off
	global_load_dwordx4 v[86:89], v[22:23], off offset:16
	v_lshl_add_u64 v[18:19], s[60:61], 0, v[0:1]
	v_add_co_u32_e64 v18, s[38:39], s57, v18
	v_xor_b32_e32 v114, 4, v227
	s_nop 0
	v_addc_co_u32_e64 v19, s[38:39], 0, v19, s[38:39]
	global_load_dwordx4 v[90:93], v[18:19], off offset:1024
	v_lshl_add_u64 v[18:19], v[104:105], 0, s[42:43]
	v_lshl_add_u64 v[22:23], v[18:19], 0, s[54:55]
	global_load_dwordx4 v[62:65], v[18:19], off offset:16
	global_load_dwordx4 v[74:77], v[18:19], off
	v_add_co_u32_e64 v18, s[38:39], s56, v18
	v_xor_b32_e32 v115, 8, v227
	s_nop 0
	v_addc_co_u32_e64 v19, s[38:39], 0, v19, s[38:39]
	global_load_dwordx4 v[78:81], v[18:19], off
	global_load_dwordx4 v[66:69], v[22:23], off offset:16
	v_lshl_add_u64 v[18:19], s[64:65], 0, v[0:1]
	v_add_co_u32_e64 v18, s[38:39], s57, v18
	v_xor_b32_e32 v116, 16, v227
	s_nop 0
	v_addc_co_u32_e64 v19, s[38:39], 0, v19, s[38:39]
	global_load_dwordx4 v[70:73], v[18:19], off offset:1024
	v_lshl_add_u64 v[18:19], v[104:105], 0, s[40:41]
	v_lshl_add_u64 v[22:23], v[18:19], 0, s[54:55]
	global_load_dwordx4 v[42:45], v[18:19], off offset:16
	global_load_dwordx4 v[54:57], v[18:19], off
	v_add_co_u32_e64 v18, s[38:39], s56, v18
	v_xor_b32_e32 v118, 32, v227
	s_nop 0
	v_addc_co_u32_e64 v19, s[38:39], 0, v19, s[38:39]
	global_load_dwordx4 v[58:61], v[18:19], off
	global_load_dwordx4 v[46:49], v[22:23], off offset:16
	v_lshl_add_u64 v[18:19], s[66:67], 0, v[0:1]
	v_add_co_u32_e64 v18, s[38:39], s57, v18
	s_mov_b32 s63, 4
	s_nop 0
	v_addc_co_u32_e64 v19, s[38:39], 0, v19, s[38:39]
	global_load_dwordx4 v[50:53], v[18:19], off offset:1024
	v_lshl_add_u64 v[18:19], v[104:105], 0, s[0:1]
	v_lshl_add_u64 v[26:27], v[18:19], 0, s[54:55]
	global_load_dwordx4 v[22:25], v[18:19], off offset:16
	global_load_dwordx4 v[34:37], v[18:19], off
	v_add_co_u32_e64 v18, s[38:39], s56, v18
	s_and_b64 vcc, exec, vcc
	s_nop 0
	v_addc_co_u32_e64 v19, s[38:39], 0, v19, s[38:39]
	global_load_dwordx4 v[38:41], v[18:19], off
	s_nop 0
	global_load_dwordx4 v[26:29], v[26:27], off offset:16
	v_lshl_add_u64 v[18:19], s[70:71], 0, v[0:1]
	v_add_co_u32_e64 v18, s[38:39], s57, v18
	s_waitcnt vmcnt(18)
	v_and_b32_e32 v138, 0xffff0000, v82
	s_waitcnt vmcnt(17)
	v_lshlrev_b32_e32 v124, 16, v95
	v_lshlrev_b32_e32 v119, 16, v96
	v_and_b32_e32 v129, 0xffff0000, v96
	v_and_b32_e32 v96, 0xffff0000, v95
	v_addc_co_u32_e64 v19, s[38:39], 0, v19, s[38:39]
	s_waitcnt vmcnt(16)
	v_lshlrev_b32_e32 v121, 16, v100
	v_and_b32_e32 v131, 0xffff0000, v100
	s_waitcnt vmcnt(15)
	v_lshlrev_b32_e32 v100, 16, v86
	v_and_b32_e32 v140, 0xffff0000, v86
	v_lshlrev_b32_e32 v120, 16, v98
	v_and_b32_e32 v130, 0xffff0000, v98
	v_lshlrev_b32_e32 v98, 16, v82
	s_waitcnt vmcnt(14)
	v_lshlrev_b32_e32 v122, 16, v90
	v_mul_f32_e32 v86, 0x3d372713, v122
	v_lshlrev_b32_e32 v136, 16, v87
	v_and_b32_e32 v82, 0xffff0000, v87
	v_mul_f32_e32 v86, v86, v122
	v_mov_b32_e32 v87, v122
	v_lshlrev_b32_e32 v123, 16, v91
	v_fmac_f32_e32 v87, v86, v87
	v_mul_f32_e32 v86, 0x3f4c422a, v87
	v_mul_f32_e32 v87, 0x3d372713, v123
	v_lshlrev_b32_e32 v127, 16, v101
	v_and_b32_e32 v95, 0xffff0000, v101
	v_lshlrev_b32_e32 v101, 16, v88
	v_and_b32_e32 v141, 0xffff0000, v88
	v_mul_f32_e32 v87, v87, v123
	v_mov_b32_e32 v88, v123
	v_fmac_f32_e32 v88, v87, v88
	v_mul_f32_e32 v87, 0x3f4c422a, v88
	v_add_f32_e32 v86, v86, v86
	v_add_f32_e32 v87, v87, v87
	v_mul_f32_e32 v86, 0x3fb8aa3b, v86
	v_mul_f32_e32 v87, 0x3fb8aa3b, v87
	v_exp_f32_e32 v86, v86
	v_exp_f32_e32 v87, v87
	global_load_dwordx4 v[30:33], v[18:19], off offset:1024
	v_and_b32_e32 v18, 64, v227
	v_add_u32_e32 v117, 64, v18
	v_xor_b32_e32 v18, 1, v227
	v_cmp_lt_i32_e64 s[38:39], v18, v117
	v_xor_b32_e32 v19, 2, v227
	v_add_f32_e32 v86, 1.0, v86
	v_add_f32_e32 v87, 1.0, v87
	v_cndmask_b32_e64 v18, v227, v18, s[38:39]
	v_cmp_lt_i32_e64 s[38:39], v19, v117
	v_rcp_f32_e32 v86, v86
	v_rcp_f32_e32 v87, v87
	v_cndmask_b32_e64 v19, v227, v19, s[38:39]
	v_cmp_lt_i32_e64 s[38:39], v114, v117
	v_lshlrev_b32_e32 v126, 16, v99
	v_pk_fma_f32 v[86:87], v[86:87], 2.0, 1.0 op_sel_hi:[1,0,0] neg_lo:[1,0,0] neg_hi:[1,0,0]
	v_cndmask_b32_e64 v114, v227, v114, s[38:39]
; __device__ __forceinline__ void lru_finish3(const Args& a, int l, int bx, int G, LAS unsigned char* lds) {
;     ...
;                 for (int i = 0; i < 8; ++i) {
;                     const unsigned fw = i < 4 ? f0[q][i & 3] : f1[q][i & 3], bw = i < 4 ? b0[q][i & 3] : b1[q][i & 3], gw2 = gq[q][i >> 1];
;                     const float cfi = i < 4 ? cf0[i & 3] : cf1[i & 3], cbi = i < 4 ? cb0[i & 3] : cb1[i & 3];
;                     const float hlf = __builtin_bit_cast(float, fw << 16), pf_ = __builtin_bit_cast(float, fw & 0xffff0000u);
;                     const float hlb = __builtin_bit_cast(float, bw << 16), pb_ = __builtin_bit_cast(float, bw & 0xffff0000u);
;                     const float g = __builtin_bit_cast(float, (i & 1) ? (gw2 & 0xffff0000u) : (gw2 << 16));
;                     y[i] = gelu_tanh(g) * ((hlf + pf_ * cfi) + (hlb + pb_ * cbi)); s += y[i] * y[i]; }
;                 s = wave_sum(s); const float rs = __builtin_amdgcn_rsqf(s * (1.f / 512.f) + 1e-6f);
	v_cmp_lt_i32_e64 s[38:39], v115, v117
	v_and_b32_e32 v128, 0xffff0000, v94
	v_lshlrev_b32_e32 v134, 16, v83
	v_cndmask_b32_e64 v115, v227, v115, s[38:39]
	v_cmp_lt_i32_e64 s[38:39], v116, v117
	v_and_b32_e32 v139, 0xffff0000, v84
	v_lshlrev_b32_e32 v137, 16, v89
	v_cndmask_b32_e64 v116, v227, v116, s[38:39]
	v_cmp_lt_i32_e64 s[38:39], v118, v117
	v_pk_add_f32 v[86:87], v[86:87], 1.0 op_sel_hi:[1,0]
	v_and_b32_e32 v90, 0xffff0000, v90
	v_cndmask_b32_e64 v117, v227, v118, s[38:39]
	v_lshlrev_b32_e32 v118, 16, v94
	v_and_b32_e32 v94, 0xffff0000, v99
	v_lshlrev_b32_e32 v99, 16, v84
	v_and_b32_e32 v84, 0xffff0000, v83
	v_and_b32_e32 v83, 0xffff0000, v89
	v_pk_mul_f32 v[88:89], v[122:123], 0.5 op_sel_hi:[1,0]
	v_and_b32_e32 v91, 0xffff0000, v91
	v_pk_mul_f32 v[86:87], v[88:89], v[86:87]
	v_pk_fma_f32 v[88:89], v[8:9], v[128:129], v[118:119]
	v_pk_fma_f32 v[118:119], v[12:13], v[130:131], v[120:121]
	v_mov_b32_e32 v120, v91
	v_pk_add_f32 v[88:89], v[88:89], v[118:119]
	v_mul_f32_e32 v118, 0x3d372713, v90
	v_mul_f32_e32 v118, v118, v90
	v_mov_b32_e32 v119, v90
	v_fmac_f32_e32 v119, v118, v119
	v_mul_f32_e32 v118, 0x3f4c422a, v119
	v_mul_f32_e32 v119, 0x3d372713, v91
	v_mul_f32_e32 v119, v119, v91
	v_fmac_f32_e32 v120, v119, v120
	v_mul_f32_e32 v119, 0x3f4c422a, v120
	v_add_f32_e32 v118, v118, v118
	v_add_f32_e32 v119, v119, v119
	v_mul_f32_e32 v118, 0x3fb8aa3b, v118
	v_mul_f32_e32 v119, 0x3fb8aa3b, v119
	v_exp_f32_e32 v118, v118
	v_exp_f32_e32 v119, v119
	v_lshlrev_b32_e32 v125, 16, v97
	v_and_b32_e32 v97, 0xffff0000, v97
	v_add_f32_e32 v118, 1.0, v118
	v_add_f32_e32 v119, 1.0, v119
	v_rcp_f32_e32 v118, v118
	v_rcp_f32_e32 v119, v119
	v_lshlrev_b32_e32 v132, 16, v92
	v_pk_fma_f32 v[96:97], v[110:111], v[96:97], v[124:125]
	v_pk_fma_f32 v[94:95], v[112:113], v[94:95], v[126:127]
	v_lshlrev_b32_e32 v133, 16, v93
	v_pk_add_f32 v[94:95], v[96:97], v[94:95]
	v_mul_f32_e32 v96, 0x3d372713, v132
	v_mul_f32_e32 v96, v96, v132
	v_mov_b32_e32 v97, v132
	v_pk_fma_f32 v[118:119], v[118:119], 2.0, 1.0 op_sel_hi:[1,0,0] neg_lo:[1,0,0] neg_hi:[1,0,0]
	v_fmac_f32_e32 v97, v96, v97
	v_pk_mul_f32 v[90:91], v[90:91], 0.5 op_sel_hi:[1,0]
	v_pk_add_f32 v[118:119], v[118:119], 1.0 op_sel_hi:[1,0]
	v_mul_f32_e32 v96, 0x3f4c422a, v97
	v_mul_f32_e32 v97, 0x3d372713, v133
	v_pk_mul_f32 v[90:91], v[90:91], v[118:119]
	v_mul_f32_e32 v97, v97, v133
	v_mov_b32_e32 v118, v133
	v_fmac_f32_e32 v118, v97, v118
	v_mul_f32_e32 v97, 0x3f4c422a, v118
	v_add_f32_e32 v96, v96, v96
	v_add_f32_e32 v97, v97, v97
	v_mul_f32_e32 v96, 0x3fb8aa3b, v96
	v_mul_f32_e32 v97, 0x3fb8aa3b, v97
	v_exp_f32_e32 v96, v96
	v_exp_f32_e32 v97, v97
	v_pk_mul_f32 v[118:119], v[132:133], 0.5 op_sel_hi:[1,0]
	v_pk_fma_f32 v[98:99], v[16:17], v[138:139], v[98:99]
	v_add_f32_e32 v96, 1.0, v96
	v_add_f32_e32 v97, 1.0, v97
	v_rcp_f32_e32 v96, v96
	v_rcp_f32_e32 v97, v97
	v_pk_fma_f32 v[100:101], v[20:21], v[140:141], v[100:101]
	v_and_b32_e32 v92, 0xffff0000, v92
	v_pk_add_f32 v[98:99], v[98:99], v[100:101]
	v_pk_fma_f32 v[96:97], v[96:97], 2.0, 1.0 op_sel_hi:[1,0,0] neg_lo:[1,0,0] neg_hi:[1,0,0]
	v_and_b32_e32 v93, 0xffff0000, v93
	v_pk_add_f32 v[96:97], v[96:97], 1.0 op_sel_hi:[1,0]
	v_mov_b32_e32 v100, v93
	v_pk_mul_f32 v[96:97], v[118:119], v[96:97]
	v_pk_mul_f32 v[86:87], v[88:89], v[86:87]
	v_pk_mul_f32 v[96:97], v[98:99], v[96:97]
	v_mul_f32_e32 v98, 0x3d372713, v92
	v_mul_f32_e32 v98, v98, v92
	v_mov_b32_e32 v99, v92
	v_fmac_f32_e32 v99, v98, v99
	v_mul_f32_e32 v98, 0x3f4c422a, v99
	v_mul_f32_e32 v99, 0x3d372713, v93
	v_mul_f32_e32 v99, v99, v93
	v_fmac_f32_e32 v100, v99, v100
	v_mul_f32_e32 v99, 0x3f4c422a, v100
	v_add_f32_e32 v98, v98, v98
	v_add_f32_e32 v99, v99, v99
	v_mul_f32_e32 v98, 0x3fb8aa3b, v98
	v_mul_f32_e32 v99, 0x3fb8aa3b, v99
	v_exp_f32_e32 v98, v98
	v_exp_f32_e32 v99, v99
	v_pk_mul_f32 v[90:91], v[94:95], v[90:91]
	v_lshlrev_b32_e32 v135, 16, v85
	v_add_f32_e32 v98, 1.0, v98
	v_add_f32_e32 v99, 1.0, v99
	v_rcp_f32_e32 v98, v98
	v_rcp_f32_e32 v99, v99
	v_and_b32_e32 v85, 0xffff0000, v85
	v_pk_mul_f32 v[88:89], v[86:87], v[86:87]
	v_pk_mul_f32 v[94:95], v[90:91], v[90:91]
	v_pk_fma_f32 v[98:99], v[98:99], 2.0, 1.0 op_sel_hi:[1,0,0] neg_lo:[1,0,0] neg_hi:[1,0,0]
	v_pk_mul_f32 v[92:93], v[92:93], 0.5 op_sel_hi:[1,0]
	v_pk_add_f32 v[98:99], v[98:99], 1.0 op_sel_hi:[1,0]
	v_pk_fma_f32 v[84:85], v[10:11], v[84:85], v[134:135]
	v_pk_fma_f32 v[82:83], v[14:15], v[82:83], v[136:137]
	v_add_f32_e32 v88, v88, v94
	v_pk_mul_f32 v[92:93], v[92:93], v[98:99]
	v_pk_add_f32 v[82:83], v[84:85], v[82:83]
	v_add_f32_e32 v88, v89, v88
	v_pk_mul_f32 v[82:83], v[82:83], v[92:93]
	v_add_f32_e32 v88, v95, v88
	v_mov_b32_e32 v84, v83
	v_mov_b32_e32 v85, v97
	v_fmac_f32_e32 v88, v96, v96
	v_pk_mul_f32 v[84:85], v[84:85], v[84:85]
	v_fmac_f32_e32 v88, v82, v82
	v_add_f32_e32 v85, v85, v88
	v_lshlrev_b32_e32 v18, 2, v18
	v_add_f32_e32 v84, v84, v85
	ds_bpermute_b32 v85, v18, v84
	v_lshlrev_b32_e32 v19, 2, v19
	v_lshlrev_b32_e32 v114, 2, v114
	v_lshlrev_b32_e32 v115, 2, v115
	v_lshlrev_b32_e32 v116, 2, v116
	s_waitcnt lgkmcnt(0)
	v_add_f32_e32 v84, v84, v85
	ds_bpermute_b32 v85, v19, v84
	v_lshlrev_b32_e32 v117, 2, v117
	s_waitcnt vmcnt(12)
	v_and_b32_e32 v95, 0xffff0000, v80
	s_waitcnt vmcnt(11)
	v_and_b32_e32 v120, 0xffff0000, v66
	s_waitcnt lgkmcnt(0)
	v_add_f32_e32 v84, v84, v85
	ds_bpermute_b32 v85, v114, v84
	v_and_b32_e32 v94, 0xffff0000, v78
	v_lshlrev_b32_e32 v100, 16, v67
	v_and_b32_e32 v118, 0xffff0000, v62
	v_and_b32_e32 v121, 0xffff0000, v68
	s_waitcnt lgkmcnt(0)
	v_add_f32_e32 v84, v84, v85
	ds_bpermute_b32 v85, v115, v84
	v_lshlrev_b32_e32 v98, 16, v63
	v_and_b32_e32 v119, 0xffff0000, v64
	v_lshlrev_b32_e32 v101, 16, v69
	v_lshlrev_b32_e32 v99, 16, v65
	s_waitcnt lgkmcnt(0)
; __device__ __forceinline__ unsigned pk2(float lo, float hi) { return f2bf(lo) | (f2bf(hi) << 16); }
; __device__ __forceinline__ void lru_finish3(const Args& a, int l, int bx, int G, LAS unsigned char* lds) {
;     ...
;                 for (int i = 0; i < 8; ++i) {
;                     const unsigned fw = i < 4 ? f0[q][i & 3] : f1[q][i & 3], bw = i < 4 ? b0[q][i & 3] : b1[q][i & 3], gw2 = gq[q][i >> 1];
;                     const float cfi = i < 4 ? cf0[i & 3] : cf1[i & 3], cbi = i < 4 ? cb0[i & 3] : cb1[i & 3];
;                     const float hlf = __builtin_bit_cast(float, fw << 16), pf_ = __builtin_bit_cast(float, fw & 0xffff0000u);
;                     const float hlb = __builtin_bit_cast(float, bw << 16), pb_ = __builtin_bit_cast(float, bw & 0xffff0000u);
;                     const float g = __builtin_bit_cast(float, (i & 1) ? (gw2 & 0xffff0000u) : (gw2 << 16));
;                     y[i] = gelu_tanh(g) * ((hlf + pf_ * cfi) + (hlb + pb_ * cbi)); s += y[i] * y[i]; }
;                 s = wave_sum(s); const float rs = __builtin_amdgcn_rsqf(s * (1.f / 512.f) + 1e-6f);
;                 u32x4 o; o.x = pk2(y[0] * rs * gn0.x, y[1] * rs * gn0.y); o.y = pk2(y[2] * rs * gn0.z, y[3] * rs * gn0.w);
;                 o.z = pk2(y[4] * rs * gn1.x, y[5] * rs * gn1.y); o.w = pk2(y[6] * rs * gn1.z, y[7] * rs * gn1.w);
;                 *(u32x4*)(Y + row * D + lane * 8) = o; }
	v_add_f32_e32 v84, v84, v85
	ds_bpermute_b32 v85, v116, v84
	v_and_b32_e32 v65, 0xffff0000, v65
	s_waitcnt lgkmcnt(0)
	v_add_f32_e32 v84, v84, v85
	ds_bpermute_b32 v85, v117, v84
	s_waitcnt lgkmcnt(0)
	v_add_f32_e32 v84, v84, v85
	v_fmamk_f32 v84, v84, 0x3b000000, v229
	v_rsq_f32_e32 v84, v84
	s_nop 0
	v_pk_mul_f32 v[88:89], v[90:91], v[84:85] op_sel_hi:[1,0]
	v_pk_mul_f32 v[82:83], v[82:83], v[84:85] op_sel_hi:[1,0]
	v_pk_mul_f32 v[86:87], v[86:87], v[84:85] op_sel_hi:[1,0]
	v_pk_mul_f32 v[88:89], v[108:109], v[88:89]
	v_pk_mul_f32 v[90:91], v[96:97], v[84:85] op_sel_hi:[1,0]
	v_pk_mul_f32 v[82:83], v[4:5], v[82:83]
	v_pk_mul_f32 v[86:87], v[2:3], v[86:87]
	v_pk_mul_f32 v[90:91], v[6:7], v[90:91]
	v_bfe_u32 v84, v83, 16, 1
	v_bfe_u32 v85, v82, 16, 1
	v_bfe_u32 v92, v89, 16, 1
	v_bfe_u32 v93, v88, 16, 1
	v_add3_u32 v88, v88, v93, s91
	v_add3_u32 v89, v89, v92, s91
	v_add3_u32 v82, v82, v85, s91
	v_add3_u32 v83, v83, v84, s91
	v_bfe_u32 v84, v86, 16, 1
	v_bfe_u32 v85, v87, 16, 1
	v_bfe_u32 v92, v90, 16, 1
	v_bfe_u32 v93, v91, 16, 1
	v_add3_u32 v91, v91, v93, s91
	v_add3_u32 v90, v90, v92, s91
	v_add3_u32 v85, v87, v85, s91
	v_add3_u32 v84, v86, v84, s91
	v_lshrrev_b32_e32 v86, 16, v84
	v_lshrrev_b32_e32 v87, 16, v85
	v_lshrrev_b32_e32 v84, 16, v90
	v_lshrrev_b32_e32 v85, 16, v91
	v_and_or_b32 v85, v83, s35, v85
	v_and_or_b32 v84, v82, s35, v84
	v_and_or_b32 v83, v89, s35, v87
	v_and_or_b32 v82, v88, s35, v86
	v_lshl_add_u64 v[86:87], v[106:107], 0, s[44:45]
	global_store_dwordx4 v[86:87], v[82:85], off sc1
	s_waitcnt vmcnt(11)
	v_lshlrev_b32_e32 v86, 16, v70
	v_lshlrev_b32_e32 v87, 16, v71
	v_lshlrev_b32_e32 v85, 16, v80
	v_lshlrev_b32_e32 v80, 16, v66
	v_mul_f32_e32 v66, 0x3d372713, v86
	v_lshlrev_b32_e32 v84, 16, v78
	v_lshlrev_b32_e32 v78, 16, v62
	v_and_b32_e32 v62, 0xffff0000, v67
	v_mul_f32_e32 v66, v66, v86
	v_mov_b32_e32 v67, v86
	v_fmac_f32_e32 v67, v66, v67
	v_mul_f32_e32 v66, 0x3f4c422a, v67
	v_mul_f32_e32 v67, 0x3d372713, v87
	v_lshlrev_b32_e32 v88, 16, v75
	v_lshlrev_b32_e32 v83, 16, v76
	v_and_b32_e32 v93, 0xffff0000, v76
	v_and_b32_e32 v76, 0xffff0000, v75
	v_lshlrev_b32_e32 v91, 16, v81
	v_and_b32_e32 v75, 0xffff0000, v81
	v_lshlrev_b32_e32 v81, 16, v68
	v_mul_f32_e32 v67, v67, v87
	v_mov_b32_e32 v68, v87
	v_fmac_f32_e32 v68, v67, v68
	v_mul_f32_e32 v67, 0x3f4c422a, v68
	v_add_f32_e32 v66, v66, v66
	v_add_f32_e32 v67, v67, v67
	v_mul_f32_e32 v66, 0x3fb8aa3b, v66
	v_mul_f32_e32 v67, 0x3fb8aa3b, v67
	v_exp_f32_e32 v66, v66
	v_exp_f32_e32 v67, v67
	v_lshlrev_b32_e32 v82, 16, v74
	v_lshlrev_b32_e32 v90, 16, v79
	v_add_f32_e32 v66, 1.0, v66
	v_add_f32_e32 v67, 1.0, v67
	v_rcp_f32_e32 v66, v66
	v_rcp_f32_e32 v67, v67
	v_and_b32_e32 v92, 0xffff0000, v74
	v_and_b32_e32 v74, 0xffff0000, v79
	v_lshlrev_b32_e32 v79, 16, v64
	v_pk_fma_f32 v[66:67], v[66:67], 2.0, 1.0 op_sel_hi:[1,0,0] neg_lo:[1,0,0] neg_hi:[1,0,0]
	v_and_b32_e32 v64, 0xffff0000, v63
	v_and_b32_e32 v63, 0xffff0000, v69
	v_pk_mul_f32 v[68:69], v[86:87], 0.5 op_sel_hi:[1,0]
	v_pk_add_f32 v[66:67], v[66:67], 1.0 op_sel_hi:[1,0]
	v_and_b32_e32 v70, 0xffff0000, v70
	v_pk_mul_f32 v[66:67], v[68:69], v[66:67]
	v_pk_fma_f32 v[68:69], v[8:9], v[92:93], v[82:83]
	v_pk_fma_f32 v[82:83], v[12:13], v[94:95], v[84:85]
	v_and_b32_e32 v71, 0xffff0000, v71
	v_pk_add_f32 v[68:69], v[68:69], v[82:83]
	v_mul_f32_e32 v82, 0x3d372713, v70
	v_mul_f32_e32 v82, v82, v70
	v_mov_b32_e32 v83, v70
	v_fmac_f32_e32 v83, v82, v83
	v_mul_f32_e32 v82, 0x3f4c422a, v83
	v_mul_f32_e32 v83, 0x3d372713, v71
	v_mul_f32_e32 v83, v83, v71
	v_mov_b32_e32 v84, v71
	v_fmac_f32_e32 v84, v83, v84
	v_mul_f32_e32 v83, 0x3f4c422a, v84
	v_add_f32_e32 v82, v82, v82
	v_add_f32_e32 v83, v83, v83
	v_mul_f32_e32 v82, 0x3fb8aa3b, v82
	v_mul_f32_e32 v83, 0x3fb8aa3b, v83
	v_exp_f32_e32 v82, v82
	v_exp_f32_e32 v83, v83
	v_lshlrev_b32_e32 v89, 16, v77
	v_and_b32_e32 v77, 0xffff0000, v77
	v_add_f32_e32 v82, 1.0, v82
	v_add_f32_e32 v83, 1.0, v83
	v_rcp_f32_e32 v82, v82
	v_rcp_f32_e32 v83, v83
	v_lshlrev_b32_e32 v96, 16, v72
	v_pk_fma_f32 v[76:77], v[110:111], v[76:77], v[88:89]
	v_pk_fma_f32 v[74:75], v[112:113], v[74:75], v[90:91]
	v_lshlrev_b32_e32 v97, 16, v73
	v_pk_add_f32 v[74:75], v[76:77], v[74:75]
	v_mul_f32_e32 v76, 0x3d372713, v96
	v_mul_f32_e32 v76, v76, v96
	v_mov_b32_e32 v77, v96
	v_pk_fma_f32 v[82:83], v[82:83], 2.0, 1.0 op_sel_hi:[1,0,0] neg_lo:[1,0,0] neg_hi:[1,0,0]
	v_fmac_f32_e32 v77, v76, v77
	v_pk_mul_f32 v[70:71], v[70:71], 0.5 op_sel_hi:[1,0]
	v_pk_add_f32 v[82:83], v[82:83], 1.0 op_sel_hi:[1,0]
	v_mul_f32_e32 v76, 0x3f4c422a, v77
	v_mul_f32_e32 v77, 0x3d372713, v97
	v_pk_mul_f32 v[70:71], v[70:71], v[82:83]
	v_mul_f32_e32 v77, v77, v97
	v_mov_b32_e32 v82, v97
	v_fmac_f32_e32 v82, v77, v82
	v_mul_f32_e32 v77, 0x3f4c422a, v82
	v_add_f32_e32 v76, v76, v76
	v_add_f32_e32 v77, v77, v77
	v_mul_f32_e32 v76, 0x3fb8aa3b, v76
	v_mul_f32_e32 v77, 0x3fb8aa3b, v77
	v_exp_f32_e32 v76, v76
	v_exp_f32_e32 v77, v77
	v_pk_mul_f32 v[82:83], v[96:97], 0.5 op_sel_hi:[1,0]
	v_pk_fma_f32 v[78:79], v[16:17], v[118:119], v[78:79]
	v_add_f32_e32 v76, 1.0, v76
	v_add_f32_e32 v77, 1.0, v77
	v_rcp_f32_e32 v76, v76
	v_rcp_f32_e32 v77, v77
	v_pk_fma_f32 v[80:81], v[20:21], v[120:121], v[80:81]
	v_and_b32_e32 v72, 0xffff0000, v72
	v_pk_add_f32 v[78:79], v[78:79], v[80:81]
	v_pk_fma_f32 v[76:77], v[76:77], 2.0, 1.0 op_sel_hi:[1,0,0] neg_lo:[1,0,0] neg_hi:[1,0,0]
	v_and_b32_e32 v73, 0xffff0000, v73
	v_pk_add_f32 v[76:77], v[76:77], 1.0 op_sel_hi:[1,0]
	v_mov_b32_e32 v80, v73
	v_pk_mul_f32 v[76:77], v[82:83], v[76:77]
	v_pk_mul_f32 v[66:67], v[68:69], v[66:67]
	v_pk_mul_f32 v[76:77], v[78:79], v[76:77]
	v_mul_f32_e32 v78, 0x3d372713, v72
; __device__ __forceinline__ unsigned pk2(float lo, float hi) { return f2bf(lo) | (f2bf(hi) << 16); }
; __device__ __forceinline__ void lru_finish3(const Args& a, int l, int bx, int G, LAS unsigned char* lds) {
;     ...
;                 for (int i = 0; i < 8; ++i) {
;                     const unsigned fw = i < 4 ? f0[q][i & 3] : f1[q][i & 3], bw = i < 4 ? b0[q][i & 3] : b1[q][i & 3], gw2 = gq[q][i >> 1];
;                     const float cfi = i < 4 ? cf0[i & 3] : cf1[i & 3], cbi = i < 4 ? cb0[i & 3] : cb1[i & 3];
;                     const float hlf = __builtin_bit_cast(float, fw << 16), pf_ = __builtin_bit_cast(float, fw & 0xffff0000u);
;                     const float hlb = __builtin_bit_cast(float, bw << 16), pb_ = __builtin_bit_cast(float, bw & 0xffff0000u);
;                     const float g = __builtin_bit_cast(float, (i & 1) ? (gw2 & 0xffff0000u) : (gw2 << 16));
;                     y[i] = gelu_tanh(g) * ((hlf + pf_ * cfi) + (hlb + pb_ * cbi)); s += y[i] * y[i]; }
;                 s = wave_sum(s); const float rs = __builtin_amdgcn_rsqf(s * (1.f / 512.f) + 1e-6f);
;                 u32x4 o; o.x = pk2(y[0] * rs * gn0.x, y[1] * rs * gn0.y); o.y = pk2(y[2] * rs * gn0.z, y[3] * rs * gn0.w);
;                 o.z = pk2(y[4] * rs * gn1.x, y[5] * rs * gn1.y); o.w = pk2(y[6] * rs * gn1.z, y[7] * rs * gn1.w);
;                 *(u32x4*)(Y + row * D + lane * 8) = o; }
	v_mul_f32_e32 v78, v78, v72
	v_mov_b32_e32 v79, v72
	v_fmac_f32_e32 v79, v78, v79
	v_mul_f32_e32 v78, 0x3f4c422a, v79
	v_mul_f32_e32 v79, 0x3d372713, v73
	v_mul_f32_e32 v79, v79, v73
	v_fmac_f32_e32 v80, v79, v80
	v_mul_f32_e32 v79, 0x3f4c422a, v80
	v_add_f32_e32 v78, v78, v78
	v_add_f32_e32 v79, v79, v79
	v_mul_f32_e32 v78, 0x3fb8aa3b, v78
	v_mul_f32_e32 v79, 0x3fb8aa3b, v79
	v_exp_f32_e32 v78, v78
	v_exp_f32_e32 v79, v79
	v_pk_mul_f32 v[70:71], v[74:75], v[70:71]
	v_pk_mul_f32 v[68:69], v[66:67], v[66:67]
	v_add_f32_e32 v78, 1.0, v78
	v_add_f32_e32 v79, 1.0, v79
	v_rcp_f32_e32 v78, v78
	v_rcp_f32_e32 v79, v79
	v_pk_mul_f32 v[74:75], v[70:71], v[70:71]
	v_pk_mul_f32 v[72:73], v[72:73], 0.5 op_sel_hi:[1,0]
	v_pk_fma_f32 v[64:65], v[10:11], v[64:65], v[98:99]
	v_pk_fma_f32 v[78:79], v[78:79], 2.0, 1.0 op_sel_hi:[1,0,0] neg_lo:[1,0,0] neg_hi:[1,0,0]
	v_pk_fma_f32 v[62:63], v[14:15], v[62:63], v[100:101]
	v_pk_add_f32 v[78:79], v[78:79], 1.0 op_sel_hi:[1,0]
	v_add_f32_e32 v68, v68, v74
	v_pk_mul_f32 v[72:73], v[72:73], v[78:79]
	v_pk_add_f32 v[62:63], v[64:65], v[62:63]
	v_add_f32_e32 v68, v69, v68
	v_pk_mul_f32 v[62:63], v[62:63], v[72:73]
	v_add_f32_e32 v68, v75, v68
	v_mov_b32_e32 v64, v63
	v_mov_b32_e32 v65, v77
	v_fmac_f32_e32 v68, v76, v76
	v_pk_mul_f32 v[64:65], v[64:65], v[64:65]
	v_fmac_f32_e32 v68, v62, v62
	v_add_f32_e32 v65, v65, v68
	v_add_f32_e32 v64, v64, v65
	ds_bpermute_b32 v65, v18, v64
	s_waitcnt vmcnt(8)
	v_and_b32_e32 v75, 0xffff0000, v60
	s_waitcnt vmcnt(7)
	v_and_b32_e32 v84, 0xffff0000, v46
	v_and_b32_e32 v74, 0xffff0000, v58
	v_lshlrev_b32_e32 v80, 16, v47
	s_waitcnt lgkmcnt(0)
	v_add_f32_e32 v64, v64, v65
	ds_bpermute_b32 v65, v19, v64
	v_and_b32_e32 v82, 0xffff0000, v42
	v_and_b32_e32 v85, 0xffff0000, v48
	v_lshlrev_b32_e32 v78, 16, v43
	v_and_b32_e32 v83, 0xffff0000, v44
	s_waitcnt lgkmcnt(0)
	v_add_f32_e32 v64, v64, v65
	ds_bpermute_b32 v65, v114, v64
	v_lshlrev_b32_e32 v81, 16, v49
	v_lshlrev_b32_e32 v79, 16, v45
	v_and_b32_e32 v45, 0xffff0000, v45
	s_waitcnt lgkmcnt(0)
	v_add_f32_e32 v64, v64, v65
	ds_bpermute_b32 v65, v115, v64
	s_waitcnt lgkmcnt(0)
	v_add_f32_e32 v64, v64, v65
	ds_bpermute_b32 v65, v116, v64
	s_waitcnt lgkmcnt(0)
	v_add_f32_e32 v64, v64, v65
	ds_bpermute_b32 v65, v117, v64
	s_waitcnt lgkmcnt(0)
	v_add_f32_e32 v64, v64, v65
	v_fmamk_f32 v64, v64, 0x3b000000, v229
	v_rsq_f32_e32 v64, v64
	s_nop 0
	v_pk_mul_f32 v[68:69], v[70:71], v[64:65] op_sel_hi:[1,0]
	v_pk_mul_f32 v[62:63], v[62:63], v[64:65] op_sel_hi:[1,0]
	v_pk_mul_f32 v[66:67], v[66:67], v[64:65] op_sel_hi:[1,0]
	v_pk_mul_f32 v[68:69], v[108:109], v[68:69]
	v_pk_mul_f32 v[70:71], v[76:77], v[64:65] op_sel_hi:[1,0]
	v_pk_mul_f32 v[62:63], v[4:5], v[62:63]
	v_pk_mul_f32 v[66:67], v[2:3], v[66:67]
	v_pk_mul_f32 v[70:71], v[6:7], v[70:71]
	v_bfe_u32 v64, v63, 16, 1
	v_bfe_u32 v65, v62, 16, 1
	v_bfe_u32 v72, v69, 16, 1
	v_bfe_u32 v73, v68, 16, 1
	v_add3_u32 v68, v68, v73, s91
	v_add3_u32 v69, v69, v72, s91
	v_add3_u32 v62, v62, v65, s91
	v_add3_u32 v63, v63, v64, s91
	v_bfe_u32 v64, v66, 16, 1
	v_bfe_u32 v65, v67, 16, 1
	v_bfe_u32 v72, v70, 16, 1
	v_bfe_u32 v73, v71, 16, 1
	v_add3_u32 v71, v71, v73, s91
	v_add3_u32 v70, v70, v72, s91
	v_add3_u32 v65, v67, v65, s91
	v_add3_u32 v64, v66, v64, s91
	v_lshrrev_b32_e32 v66, 16, v64
	v_lshrrev_b32_e32 v67, 16, v65
	v_lshrrev_b32_e32 v64, 16, v70
	v_lshrrev_b32_e32 v65, 16, v71
	v_and_or_b32 v65, v63, s35, v65
	v_and_or_b32 v64, v62, s35, v64
	v_and_or_b32 v63, v69, s35, v67
	v_and_or_b32 v62, v68, s35, v66
	v_lshl_add_u64 v[66:67], v[106:107], 0, s[42:43]
	global_store_dwordx4 v[66:67], v[62:65], off sc1
	s_waitcnt vmcnt(7)
	v_lshlrev_b32_e32 v66, 16, v50
	v_lshlrev_b32_e32 v67, 16, v51
	v_lshlrev_b32_e32 v65, 16, v60
	v_lshlrev_b32_e32 v60, 16, v46
	v_mul_f32_e32 v46, 0x3d372713, v66
	v_lshlrev_b32_e32 v64, 16, v58
	v_lshlrev_b32_e32 v58, 16, v42
	v_and_b32_e32 v42, 0xffff0000, v47
	v_mul_f32_e32 v46, v46, v66
	v_mov_b32_e32 v47, v66
	v_fmac_f32_e32 v47, v46, v47
	v_mul_f32_e32 v46, 0x3f4c422a, v47
	v_mul_f32_e32 v47, 0x3d372713, v67
	v_lshlrev_b32_e32 v68, 16, v55
	v_lshlrev_b32_e32 v63, 16, v56
	v_and_b32_e32 v73, 0xffff0000, v56
	v_and_b32_e32 v56, 0xffff0000, v55
	v_lshlrev_b32_e32 v71, 16, v61
	v_and_b32_e32 v55, 0xffff0000, v61
	v_lshlrev_b32_e32 v61, 16, v48
	v_mul_f32_e32 v47, v47, v67
	v_mov_b32_e32 v48, v67
	v_fmac_f32_e32 v48, v47, v48
	v_mul_f32_e32 v47, 0x3f4c422a, v48
	v_add_f32_e32 v46, v46, v46
	v_add_f32_e32 v47, v47, v47
	v_mul_f32_e32 v46, 0x3fb8aa3b, v46
	v_mul_f32_e32 v47, 0x3fb8aa3b, v47
	v_exp_f32_e32 v46, v46
	v_exp_f32_e32 v47, v47
	v_lshlrev_b32_e32 v62, 16, v54
	v_lshlrev_b32_e32 v70, 16, v59
	v_add_f32_e32 v46, 1.0, v46
	v_add_f32_e32 v47, 1.0, v47
	v_rcp_f32_e32 v46, v46
	v_rcp_f32_e32 v47, v47
	v_and_b32_e32 v72, 0xffff0000, v54
	v_and_b32_e32 v54, 0xffff0000, v59
	v_lshlrev_b32_e32 v59, 16, v44
	v_pk_fma_f32 v[46:47], v[46:47], 2.0, 1.0 op_sel_hi:[1,0,0] neg_lo:[1,0,0] neg_hi:[1,0,0]
	v_and_b32_e32 v44, 0xffff0000, v43
	v_and_b32_e32 v43, 0xffff0000, v49
	v_pk_mul_f32 v[48:49], v[66:67], 0.5 op_sel_hi:[1,0]
	v_pk_add_f32 v[46:47], v[46:47], 1.0 op_sel_hi:[1,0]
	v_and_b32_e32 v50, 0xffff0000, v50
	v_pk_mul_f32 v[46:47], v[48:49], v[46:47]
	v_pk_fma_f32 v[48:49], v[8:9], v[72:73], v[62:63]
	v_pk_fma_f32 v[62:63], v[12:13], v[74:75], v[64:65]
	v_and_b32_e32 v51, 0xffff0000, v51
	v_pk_add_f32 v[48:49], v[48:49], v[62:63]
	v_mul_f32_e32 v62, 0x3d372713, v50
	v_mul_f32_e32 v62, v62, v50
	v_mov_b32_e32 v63, v50
	v_fmac_f32_e32 v63, v62, v63
	v_mul_f32_e32 v62, 0x3f4c422a, v63
	v_mul_f32_e32 v63, 0x3d372713, v51
	v_mul_f32_e32 v63, v63, v51
	v_mov_b32_e32 v64, v51
; __device__ __forceinline__ unsigned pk2(float lo, float hi) { return f2bf(lo) | (f2bf(hi) << 16); }
; __device__ __forceinline__ void lru_finish3(const Args& a, int l, int bx, int G, LAS unsigned char* lds) {
;     ...
;                 for (int i = 0; i < 8; ++i) {
;                     const unsigned fw = i < 4 ? f0[q][i & 3] : f1[q][i & 3], bw = i < 4 ? b0[q][i & 3] : b1[q][i & 3], gw2 = gq[q][i >> 1];
;                     const float cfi = i < 4 ? cf0[i & 3] : cf1[i & 3], cbi = i < 4 ? cb0[i & 3] : cb1[i & 3];
;                     const float hlf = __builtin_bit_cast(float, fw << 16), pf_ = __builtin_bit_cast(float, fw & 0xffff0000u);
;                     const float hlb = __builtin_bit_cast(float, bw << 16), pb_ = __builtin_bit_cast(float, bw & 0xffff0000u);
;                     const float g = __builtin_bit_cast(float, (i & 1) ? (gw2 & 0xffff0000u) : (gw2 << 16));
;                     y[i] = gelu_tanh(g) * ((hlf + pf_ * cfi) + (hlb + pb_ * cbi)); s += y[i] * y[i]; }
;                 s = wave_sum(s); const float rs = __builtin_amdgcn_rsqf(s * (1.f / 512.f) + 1e-6f);
;                 u32x4 o; o.x = pk2(y[0] * rs * gn0.x, y[1] * rs * gn0.y); o.y = pk2(y[2] * rs * gn0.z, y[3] * rs * gn0.w);
;                 o.z = pk2(y[4] * rs * gn1.x, y[5] * rs * gn1.y); o.w = pk2(y[6] * rs * gn1.z, y[7] * rs * gn1.w);
;                 *(u32x4*)(Y + row * D + lane * 8) = o; }
	v_fmac_f32_e32 v64, v63, v64
	v_mul_f32_e32 v63, 0x3f4c422a, v64
	v_add_f32_e32 v62, v62, v62
	v_add_f32_e32 v63, v63, v63
	v_mul_f32_e32 v62, 0x3fb8aa3b, v62
	v_mul_f32_e32 v63, 0x3fb8aa3b, v63
	v_exp_f32_e32 v62, v62
	v_exp_f32_e32 v63, v63
	v_lshlrev_b32_e32 v69, 16, v57
	v_and_b32_e32 v57, 0xffff0000, v57
	v_add_f32_e32 v62, 1.0, v62
	v_add_f32_e32 v63, 1.0, v63
	v_rcp_f32_e32 v62, v62
	v_rcp_f32_e32 v63, v63
	v_lshlrev_b32_e32 v76, 16, v52
	v_pk_fma_f32 v[56:57], v[110:111], v[56:57], v[68:69]
	v_pk_fma_f32 v[54:55], v[112:113], v[54:55], v[70:71]
	v_lshlrev_b32_e32 v77, 16, v53
	v_pk_add_f32 v[54:55], v[56:57], v[54:55]
	v_mul_f32_e32 v56, 0x3d372713, v76
	v_mul_f32_e32 v56, v56, v76
	v_mov_b32_e32 v57, v76
	v_pk_fma_f32 v[62:63], v[62:63], 2.0, 1.0 op_sel_hi:[1,0,0] neg_lo:[1,0,0] neg_hi:[1,0,0]
	v_fmac_f32_e32 v57, v56, v57
	v_pk_mul_f32 v[50:51], v[50:51], 0.5 op_sel_hi:[1,0]
	v_pk_add_f32 v[62:63], v[62:63], 1.0 op_sel_hi:[1,0]
	v_mul_f32_e32 v56, 0x3f4c422a, v57
	v_mul_f32_e32 v57, 0x3d372713, v77
	v_pk_mul_f32 v[50:51], v[50:51], v[62:63]
	v_mul_f32_e32 v57, v57, v77
	v_mov_b32_e32 v62, v77
	v_fmac_f32_e32 v62, v57, v62
	v_mul_f32_e32 v57, 0x3f4c422a, v62
	v_add_f32_e32 v56, v56, v56
	v_add_f32_e32 v57, v57, v57
	v_mul_f32_e32 v56, 0x3fb8aa3b, v56
	v_mul_f32_e32 v57, 0x3fb8aa3b, v57
	v_exp_f32_e32 v56, v56
	v_exp_f32_e32 v57, v57
	v_pk_mul_f32 v[62:63], v[76:77], 0.5 op_sel_hi:[1,0]
	v_pk_fma_f32 v[58:59], v[16:17], v[82:83], v[58:59]
	v_add_f32_e32 v56, 1.0, v56
	v_add_f32_e32 v57, 1.0, v57
	v_rcp_f32_e32 v56, v56
	v_rcp_f32_e32 v57, v57
	v_pk_fma_f32 v[60:61], v[20:21], v[84:85], v[60:61]
	v_and_b32_e32 v52, 0xffff0000, v52
	v_pk_add_f32 v[58:59], v[58:59], v[60:61]
	v_pk_fma_f32 v[56:57], v[56:57], 2.0, 1.0 op_sel_hi:[1,0,0] neg_lo:[1,0,0] neg_hi:[1,0,0]
	v_and_b32_e32 v53, 0xffff0000, v53
	v_pk_add_f32 v[56:57], v[56:57], 1.0 op_sel_hi:[1,0]
	v_mov_b32_e32 v60, v53
	v_pk_mul_f32 v[56:57], v[62:63], v[56:57]
	v_pk_mul_f32 v[46:47], v[48:49], v[46:47]
	v_pk_mul_f32 v[56:57], v[58:59], v[56:57]
	v_mul_f32_e32 v58, 0x3d372713, v52
	v_mul_f32_e32 v58, v58, v52
	v_mov_b32_e32 v59, v52
	v_fmac_f32_e32 v59, v58, v59
	v_mul_f32_e32 v58, 0x3f4c422a, v59
	v_mul_f32_e32 v59, 0x3d372713, v53
	v_mul_f32_e32 v59, v59, v53
	v_fmac_f32_e32 v60, v59, v60
	v_mul_f32_e32 v59, 0x3f4c422a, v60
	v_add_f32_e32 v58, v58, v58
	v_add_f32_e32 v59, v59, v59
	v_mul_f32_e32 v58, 0x3fb8aa3b, v58
	v_mul_f32_e32 v59, 0x3fb8aa3b, v59
	v_exp_f32_e32 v58, v58
	v_exp_f32_e32 v59, v59
	v_pk_mul_f32 v[50:51], v[54:55], v[50:51]
	v_pk_mul_f32 v[48:49], v[46:47], v[46:47]
	v_add_f32_e32 v58, 1.0, v58
	v_add_f32_e32 v59, 1.0, v59
	v_rcp_f32_e32 v58, v58
	v_rcp_f32_e32 v59, v59
	v_pk_mul_f32 v[54:55], v[50:51], v[50:51]
	v_pk_mul_f32 v[52:53], v[52:53], 0.5 op_sel_hi:[1,0]
	v_pk_fma_f32 v[44:45], v[10:11], v[44:45], v[78:79]
	v_pk_fma_f32 v[58:59], v[58:59], 2.0, 1.0 op_sel_hi:[1,0,0] neg_lo:[1,0,0] neg_hi:[1,0,0]
	v_pk_fma_f32 v[42:43], v[14:15], v[42:43], v[80:81]
	v_pk_add_f32 v[58:59], v[58:59], 1.0 op_sel_hi:[1,0]
	v_add_f32_e32 v48, v48, v54
	v_pk_mul_f32 v[52:53], v[52:53], v[58:59]
	v_pk_add_f32 v[42:43], v[44:45], v[42:43]
	v_add_f32_e32 v48, v49, v48
	v_pk_mul_f32 v[42:43], v[42:43], v[52:53]
	v_add_f32_e32 v48, v55, v48
	v_mov_b32_e32 v44, v43
	v_mov_b32_e32 v45, v57
	v_fmac_f32_e32 v48, v56, v56
	v_pk_mul_f32 v[44:45], v[44:45], v[44:45]
	v_fmac_f32_e32 v48, v42, v42
	v_add_f32_e32 v45, v45, v48
	v_add_f32_e32 v44, v44, v45
	ds_bpermute_b32 v45, v18, v44
	s_waitcnt vmcnt(4)
	v_and_b32_e32 v55, 0xffff0000, v40
	s_waitcnt vmcnt(3)
	v_and_b32_e32 v64, 0xffff0000, v26
	v_and_b32_e32 v54, 0xffff0000, v38
	v_lshlrev_b32_e32 v60, 16, v27
	s_waitcnt lgkmcnt(0)
	v_add_f32_e32 v44, v44, v45
	ds_bpermute_b32 v45, v19, v44
	v_and_b32_e32 v62, 0xffff0000, v22
	v_and_b32_e32 v65, 0xffff0000, v28
	v_lshlrev_b32_e32 v58, 16, v23
	v_and_b32_e32 v63, 0xffff0000, v24
	s_waitcnt lgkmcnt(0)
	v_add_f32_e32 v44, v44, v45
	ds_bpermute_b32 v45, v114, v44
	v_lshlrev_b32_e32 v61, 16, v29
	v_lshlrev_b32_e32 v59, 16, v25
	v_and_b32_e32 v25, 0xffff0000, v25
	s_waitcnt lgkmcnt(0)
	v_add_f32_e32 v44, v44, v45
	ds_bpermute_b32 v45, v115, v44
	s_waitcnt lgkmcnt(0)
	v_add_f32_e32 v44, v44, v45
	ds_bpermute_b32 v45, v116, v44
	s_waitcnt lgkmcnt(0)
	v_add_f32_e32 v44, v44, v45
	ds_bpermute_b32 v45, v117, v44
	s_waitcnt lgkmcnt(0)
	v_add_f32_e32 v44, v44, v45
	v_fmamk_f32 v44, v44, 0x3b000000, v229
	v_rsq_f32_e32 v44, v44
	s_nop 0
	v_pk_mul_f32 v[48:49], v[50:51], v[44:45] op_sel_hi:[1,0]
	v_pk_mul_f32 v[42:43], v[42:43], v[44:45] op_sel_hi:[1,0]
	v_pk_mul_f32 v[46:47], v[46:47], v[44:45] op_sel_hi:[1,0]
	v_pk_mul_f32 v[48:49], v[108:109], v[48:49]
	v_pk_mul_f32 v[50:51], v[56:57], v[44:45] op_sel_hi:[1,0]
	v_pk_mul_f32 v[42:43], v[4:5], v[42:43]
	v_pk_mul_f32 v[46:47], v[2:3], v[46:47]
	v_pk_mul_f32 v[50:51], v[6:7], v[50:51]
	v_bfe_u32 v44, v43, 16, 1
	v_bfe_u32 v45, v42, 16, 1
	v_bfe_u32 v52, v49, 16, 1
	v_bfe_u32 v53, v48, 16, 1
	v_add3_u32 v48, v48, v53, s91
	v_add3_u32 v49, v49, v52, s91
	v_add3_u32 v42, v42, v45, s91
	v_add3_u32 v43, v43, v44, s91
	v_bfe_u32 v44, v46, 16, 1
	v_bfe_u32 v45, v47, 16, 1
	v_bfe_u32 v52, v50, 16, 1
	v_bfe_u32 v53, v51, 16, 1
	v_add3_u32 v51, v51, v53, s91
	v_add3_u32 v50, v50, v52, s91
	v_add3_u32 v45, v47, v45, s91
	v_add3_u32 v44, v46, v44, s91
	v_lshrrev_b32_e32 v46, 16, v44
	v_lshrrev_b32_e32 v47, 16, v45
	v_lshrrev_b32_e32 v44, 16, v50
	v_lshrrev_b32_e32 v45, 16, v51
	v_and_or_b32 v45, v43, s35, v45
	v_and_or_b32 v44, v42, s35, v44
	v_and_or_b32 v43, v49, s35, v47
	v_and_or_b32 v42, v48, s35, v46
	v_lshl_add_u64 v[46:47], v[106:107], 0, s[40:41]
	global_store_dwordx4 v[46:47], v[42:45], off sc1
	s_waitcnt vmcnt(3)
; __device__ __forceinline__ void lru_finish3(const Args& a, int l, int bx, int G, LAS unsigned char* lds) {
;     ...
;                 for (int i = 0; i < 8; ++i) {
;                     const unsigned fw = i < 4 ? f0[q][i & 3] : f1[q][i & 3], bw = i < 4 ? b0[q][i & 3] : b1[q][i & 3], gw2 = gq[q][i >> 1];
;                     const float cfi = i < 4 ? cf0[i & 3] : cf1[i & 3], cbi = i < 4 ? cb0[i & 3] : cb1[i & 3];
;                     const float hlf = __builtin_bit_cast(float, fw << 16), pf_ = __builtin_bit_cast(float, fw & 0xffff0000u);
;                     const float hlb = __builtin_bit_cast(float, bw << 16), pb_ = __builtin_bit_cast(float, bw & 0xffff0000u);
;                     const float g = __builtin_bit_cast(float, (i & 1) ? (gw2 & 0xffff0000u) : (gw2 << 16));
;                     y[i] = gelu_tanh(g) * ((hlf + pf_ * cfi) + (hlb + pb_ * cbi)); s += y[i] * y[i]; }
	v_lshlrev_b32_e32 v46, 16, v30
	v_lshlrev_b32_e32 v47, 16, v31
	v_lshlrev_b32_e32 v45, 16, v40
	v_lshlrev_b32_e32 v40, 16, v26
	v_mul_f32_e32 v26, 0x3d372713, v46
	v_lshlrev_b32_e32 v44, 16, v38
	v_lshlrev_b32_e32 v38, 16, v22
	v_and_b32_e32 v22, 0xffff0000, v27
	v_mul_f32_e32 v26, v26, v46
	v_mov_b32_e32 v27, v46
	v_fmac_f32_e32 v27, v26, v27
	v_mul_f32_e32 v26, 0x3f4c422a, v27
	v_mul_f32_e32 v27, 0x3d372713, v47
	v_lshlrev_b32_e32 v48, 16, v35
	v_lshlrev_b32_e32 v43, 16, v36
	v_and_b32_e32 v53, 0xffff0000, v36
	v_and_b32_e32 v36, 0xffff0000, v35
	v_lshlrev_b32_e32 v51, 16, v41
	v_and_b32_e32 v35, 0xffff0000, v41
	v_lshlrev_b32_e32 v41, 16, v28
	v_mul_f32_e32 v27, v27, v47
	v_mov_b32_e32 v28, v47
	v_fmac_f32_e32 v28, v27, v28
	v_mul_f32_e32 v27, 0x3f4c422a, v28
	v_add_f32_e32 v26, v26, v26
	v_add_f32_e32 v27, v27, v27
	v_mul_f32_e32 v26, 0x3fb8aa3b, v26
	v_mul_f32_e32 v27, 0x3fb8aa3b, v27
	v_exp_f32_e32 v26, v26
	v_exp_f32_e32 v27, v27
	v_lshlrev_b32_e32 v42, 16, v34
	v_lshlrev_b32_e32 v50, 16, v39
	v_add_f32_e32 v26, 1.0, v26
	v_add_f32_e32 v27, 1.0, v27
	v_rcp_f32_e32 v26, v26
	v_rcp_f32_e32 v27, v27
	v_and_b32_e32 v52, 0xffff0000, v34
	v_and_b32_e32 v34, 0xffff0000, v39
	v_lshlrev_b32_e32 v39, 16, v24
	v_pk_fma_f32 v[26:27], v[26:27], 2.0, 1.0 op_sel_hi:[1,0,0] neg_lo:[1,0,0] neg_hi:[1,0,0]
	v_and_b32_e32 v24, 0xffff0000, v23
	v_and_b32_e32 v23, 0xffff0000, v29
	v_pk_mul_f32 v[28:29], v[46:47], 0.5 op_sel_hi:[1,0]
	v_pk_add_f32 v[26:27], v[26:27], 1.0 op_sel_hi:[1,0]
	v_and_b32_e32 v30, 0xffff0000, v30
	v_pk_mul_f32 v[26:27], v[28:29], v[26:27]
	v_pk_fma_f32 v[28:29], v[8:9], v[52:53], v[42:43]
	v_pk_fma_f32 v[42:43], v[12:13], v[54:55], v[44:45]
	v_and_b32_e32 v31, 0xffff0000, v31
	v_pk_add_f32 v[28:29], v[28:29], v[42:43]
	v_mul_f32_e32 v42, 0x3d372713, v30
	v_mul_f32_e32 v42, v42, v30
	v_mov_b32_e32 v43, v30
	v_fmac_f32_e32 v43, v42, v43
	v_mul_f32_e32 v42, 0x3f4c422a, v43
	v_mul_f32_e32 v43, 0x3d372713, v31
	v_mul_f32_e32 v43, v43, v31
	v_mov_b32_e32 v44, v31
	v_fmac_f32_e32 v44, v43, v44
	v_mul_f32_e32 v43, 0x3f4c422a, v44
	v_add_f32_e32 v42, v42, v42
	v_add_f32_e32 v43, v43, v43
	v_mul_f32_e32 v42, 0x3fb8aa3b, v42
	v_mul_f32_e32 v43, 0x3fb8aa3b, v43
	v_exp_f32_e32 v42, v42
	v_exp_f32_e32 v43, v43
	v_lshlrev_b32_e32 v49, 16, v37
	v_and_b32_e32 v37, 0xffff0000, v37
	v_add_f32_e32 v42, 1.0, v42
	v_add_f32_e32 v43, 1.0, v43
	v_rcp_f32_e32 v42, v42
	v_rcp_f32_e32 v43, v43
	v_lshlrev_b32_e32 v56, 16, v32
	v_pk_fma_f32 v[36:37], v[110:111], v[36:37], v[48:49]
	v_pk_fma_f32 v[34:35], v[112:113], v[34:35], v[50:51]
	v_lshlrev_b32_e32 v57, 16, v33
	v_pk_add_f32 v[34:35], v[36:37], v[34:35]
	v_mul_f32_e32 v36, 0x3d372713, v56
	v_mul_f32_e32 v36, v36, v56
	v_mov_b32_e32 v37, v56
	v_pk_fma_f32 v[42:43], v[42:43], 2.0, 1.0 op_sel_hi:[1,0,0] neg_lo:[1,0,0] neg_hi:[1,0,0]
	v_fmac_f32_e32 v37, v36, v37
	v_pk_mul_f32 v[30:31], v[30:31], 0.5 op_sel_hi:[1,0]
	v_pk_add_f32 v[42:43], v[42:43], 1.0 op_sel_hi:[1,0]
	v_mul_f32_e32 v36, 0x3f4c422a, v37
	v_mul_f32_e32 v37, 0x3d372713, v57
	v_pk_mul_f32 v[30:31], v[30:31], v[42:43]
	v_mul_f32_e32 v37, v37, v57
	v_mov_b32_e32 v42, v57
	v_fmac_f32_e32 v42, v37, v42
	v_mul_f32_e32 v37, 0x3f4c422a, v42
	v_add_f32_e32 v36, v36, v36
	v_add_f32_e32 v37, v37, v37
	v_mul_f32_e32 v36, 0x3fb8aa3b, v36
	v_mul_f32_e32 v37, 0x3fb8aa3b, v37
	v_exp_f32_e32 v36, v36
	v_exp_f32_e32 v37, v37
	v_pk_mul_f32 v[42:43], v[56:57], 0.5 op_sel_hi:[1,0]
	v_pk_fma_f32 v[38:39], v[16:17], v[62:63], v[38:39]
	v_add_f32_e32 v36, 1.0, v36
	v_add_f32_e32 v37, 1.0, v37
	v_rcp_f32_e32 v36, v36
	v_rcp_f32_e32 v37, v37
	v_pk_fma_f32 v[40:41], v[20:21], v[64:65], v[40:41]
	v_and_b32_e32 v32, 0xffff0000, v32
	v_pk_add_f32 v[38:39], v[38:39], v[40:41]
	v_pk_fma_f32 v[36:37], v[36:37], 2.0, 1.0 op_sel_hi:[1,0,0] neg_lo:[1,0,0] neg_hi:[1,0,0]
	v_and_b32_e32 v33, 0xffff0000, v33
	v_pk_add_f32 v[36:37], v[36:37], 1.0 op_sel_hi:[1,0]
	v_mov_b32_e32 v40, v33
	v_pk_mul_f32 v[36:37], v[42:43], v[36:37]
	v_pk_mul_f32 v[26:27], v[28:29], v[26:27]
	v_pk_mul_f32 v[36:37], v[38:39], v[36:37]
	v_mul_f32_e32 v38, 0x3d372713, v32
	v_mul_f32_e32 v38, v38, v32
	v_mov_b32_e32 v39, v32
	v_fmac_f32_e32 v39, v38, v39
	v_mul_f32_e32 v38, 0x3f4c422a, v39
	v_mul_f32_e32 v39, 0x3d372713, v33
	v_mul_f32_e32 v39, v39, v33
	v_fmac_f32_e32 v40, v39, v40
	v_mul_f32_e32 v39, 0x3f4c422a, v40
	v_add_f32_e32 v38, v38, v38
	v_add_f32_e32 v39, v39, v39
	v_mul_f32_e32 v38, 0x3fb8aa3b, v38
	v_mul_f32_e32 v39, 0x3fb8aa3b, v39
	v_exp_f32_e32 v38, v38
	v_exp_f32_e32 v39, v39
	v_pk_mul_f32 v[30:31], v[34:35], v[30:31]
	v_pk_mul_f32 v[28:29], v[26:27], v[26:27]
	v_add_f32_e32 v38, 1.0, v38
	v_add_f32_e32 v39, 1.0, v39
	v_rcp_f32_e32 v38, v38
	v_rcp_f32_e32 v39, v39
	v_pk_mul_f32 v[34:35], v[30:31], v[30:31]
	v_pk_mul_f32 v[32:33], v[32:33], 0.5 op_sel_hi:[1,0]
	v_pk_fma_f32 v[24:25], v[10:11], v[24:25], v[58:59]
	v_pk_fma_f32 v[38:39], v[38:39], 2.0, 1.0 op_sel_hi:[1,0,0] neg_lo:[1,0,0] neg_hi:[1,0,0]
	v_pk_fma_f32 v[22:23], v[14:15], v[22:23], v[60:61]
	v_pk_add_f32 v[38:39], v[38:39], 1.0 op_sel_hi:[1,0]
	v_add_f32_e32 v28, v28, v34
	v_pk_mul_f32 v[32:33], v[32:33], v[38:39]
	v_pk_add_f32 v[22:23], v[24:25], v[22:23]
	v_add_f32_e32 v28, v29, v28
	v_pk_mul_f32 v[22:23], v[22:23], v[32:33]
	v_add_f32_e32 v28, v35, v28
	v_mov_b32_e32 v24, v23
	v_mov_b32_e32 v25, v37
	v_fmac_f32_e32 v28, v36, v36
	v_pk_mul_f32 v[24:25], v[24:25], v[24:25]
	v_fmac_f32_e32 v28, v22, v22
	v_add_f32_e32 v25, v25, v28
	v_add_f32_e32 v24, v24, v25
	ds_bpermute_b32 v18, v18, v24
	s_waitcnt lgkmcnt(0)
; __device__ __forceinline__ unsigned pk2(float lo, float hi) { return f2bf(lo) | (f2bf(hi) << 16); }
; __device__ __forceinline__ void lru_finish3(const Args& a, int l, int bx, int G, LAS unsigned char* lds) {
;     ...
;                 s = wave_sum(s); const float rs = __builtin_amdgcn_rsqf(s * (1.f / 512.f) + 1e-6f);
;                 u32x4 o; o.x = pk2(y[0] * rs * gn0.x, y[1] * rs * gn0.y); o.y = pk2(y[2] * rs * gn0.z, y[3] * rs * gn0.w);
;                 o.z = pk2(y[4] * rs * gn1.x, y[5] * rs * gn1.y); o.w = pk2(y[6] * rs * gn1.z, y[7] * rs * gn1.w);
;                 *(u32x4*)(Y + row * D + lane * 8) = o; }
; __device__ __forceinline__ void xcd_barrier(const XcdBarrier& b) {
;     asm volatile("s_waitcnt vmcnt(0)" ::: "memory");
;     __syncthreads();
;     if (threadIdx.x == 0) {
;         unsigned* bar = b.bar;
;         __builtin_amdgcn_s_waitcnt(0);
;         unsigned nloc = b.st[0], nx = b.st[1];
	v_add_f32_e32 v18, v24, v18
	ds_bpermute_b32 v19, v19, v18
	s_waitcnt lgkmcnt(0)
	v_add_f32_e32 v18, v18, v19
	ds_bpermute_b32 v19, v114, v18
	s_waitcnt lgkmcnt(0)
	v_add_f32_e32 v18, v18, v19
	ds_bpermute_b32 v19, v115, v18
	s_waitcnt lgkmcnt(0)
	v_add_f32_e32 v18, v18, v19
	ds_bpermute_b32 v19, v116, v18
	s_waitcnt lgkmcnt(0)
	v_add_f32_e32 v18, v18, v19
	ds_bpermute_b32 v19, v117, v18
	s_waitcnt lgkmcnt(0)
	v_add_f32_e32 v18, v18, v19
	v_fmamk_f32 v18, v18, 0x3b000000, v229
	v_rsq_f32_e32 v18, v18
	s_nop 0
	v_pk_mul_f32 v[24:25], v[26:27], v[18:19] op_sel_hi:[1,0]
	v_pk_mul_f32 v[26:27], v[30:31], v[18:19] op_sel_hi:[1,0]
	v_pk_mul_f32 v[28:29], v[36:37], v[18:19] op_sel_hi:[1,0]
	v_pk_mul_f32 v[18:19], v[22:23], v[18:19] op_sel_hi:[1,0]
	v_pk_mul_f32 v[26:27], v[108:109], v[26:27]
	v_pk_mul_f32 v[18:19], v[4:5], v[18:19]
	v_pk_mul_f32 v[24:25], v[2:3], v[24:25]
	v_pk_mul_f32 v[28:29], v[6:7], v[28:29]
	v_bfe_u32 v22, v19, 16, 1
	v_bfe_u32 v23, v18, 16, 1
	v_bfe_u32 v30, v27, 16, 1
	v_bfe_u32 v31, v26, 16, 1
	v_add3_u32 v26, v26, v31, s91
	v_add3_u32 v27, v27, v30, s91
	v_add3_u32 v18, v18, v23, s91
	v_add3_u32 v19, v19, v22, s91
	v_bfe_u32 v22, v24, 16, 1
	v_bfe_u32 v23, v25, 16, 1
	v_bfe_u32 v30, v28, 16, 1
	v_bfe_u32 v31, v29, 16, 1
	v_add3_u32 v29, v29, v31, s91
	v_add3_u32 v28, v28, v30, s91
	v_add3_u32 v23, v25, v23, s91
	v_add3_u32 v22, v24, v22, s91
	v_lshrrev_b32_e32 v22, 16, v22
	v_lshrrev_b32_e32 v23, 16, v23
	v_lshrrev_b32_e32 v24, 16, v28
	v_lshrrev_b32_e32 v25, 16, v29
	v_and_or_b32 v25, v19, s35, v25
	v_and_or_b32 v24, v18, s35, v24
	v_and_or_b32 v23, v27, s35, v23
	v_and_or_b32 v22, v26, s35, v22
	v_lshl_add_u64 v[18:19], v[106:107], 0, s[0:1]
	s_mov_b64 s[0:1], 0
	global_store_dwordx4 v[18:19], v[22:25], off sc1
	s_cbranch_vccz .LBB0_310
	s_add_i32 s46, s46, s94
	s_cmpk_gt_i32 s46, 0xff
	s_cbranch_scc0 .LBB0_309
	s_mov_b32 s70, 0x10000
	s_mov_b32 s71, 0x16000
.LBB0_313:
	s_waitcnt vmcnt(0)
	s_barrier
	s_and_saveexec_b64 s[0:1], s[80:81]
	s_cbranch_execz .LBB0_365
	v_mov_b32_e32 v5, 0x2000c
	ds_read_b32 v5, v5
	s_waitcnt lgkmcnt(0)
	v_readfirstlane_b32 s4, v5
	s_cmp_lg_u32 s4, 0
	s_cbranch_scc1 .Lf3_global
	s_lshr_b32 s4, s2, 2
	s_lshl_b32 s4, s4, 8
	s_add_i32 s4, s4, 0x4000
	v_mov_b32_e32 v5, s4
	v_mov_b32_e32 v6, 1
	s_nop 0
	global_atomic_add v5, v6, s[50:51]
	s_and_b32 s4, s2, 7
	s_lshl_b32 s4, s4, 3
	s_lshr_b32 s5, s2, 3
	s_and_b32 s5, s5, 7
	s_or_b32 s4, s4, s5
	s_lshl_b32 s4, s4, 8
	s_add_i32 s4, s4, 0x4000
	v_mov_b32_e32 v5, s4
	v_readlane_b32 s4, v254, 51
	s_add_i32 s4, s4, 1
	s_lshl_b32 s4, s4, 2
	s_movk_i32 s5, 0x100

; __device__ __forceinline__ unsigned xb_add(unsigned* p, unsigned v) { return __hip_atomic_fetch_add(p, v, __ATOMIC_RELAXED, __HIP_MEMORY_SCOPE_AGENT); }
; __device__ __forceinline__ void xcd_barrier(const XcdBarrier& b) {
;     ...
;     if (threadIdx.x == 0) {
;         unsigned* bar = b.bar;
;         __builtin_amdgcn_s_waitcnt(0);
;         unsigned nloc = b.st[0], nx = b.st[1];
;         if (nloc == 0u) { xcd_barrier_complete(bar, b.x, nloc, nx); b.st[0] = nloc; b.st[1] = nx; }
;         const unsigned old = xb_add(&bar[XB_XSUB(b.x)], 1u);
;         const unsigned gen = old / nloc;
.Lf3_ok:
	buffer_inv sc1
	s_waitcnt vmcnt(0)
	s_branch .LBB0_365
.Lf3_global:
	v_readlane_b32 s4, v254, 27
	s_waitcnt vmcnt(0) expcnt(0) lgkmcnt(0)
	s_nop 0
	v_mov_b32_e32 v0, s4
	ds_read_b32 v3, v0
	v_readlane_b32 s4, v254, 28
	s_waitcnt lgkmcnt(0)
	v_cmp_ne_u32_e32 vcc, 0, v3
	v_mov_b32_e32 v0, s4
	ds_read_b32 v2, v0
	s_cbranch_vccnz .LBB0_329
	s_mov_b32 s42, 1
	s_branch .LBB0_317
